# grid barrier: the workgroup completing the top-level count bumps all XCD generation words itself (followers released one hop earlier)
# baseline (speedup 1.0000x reference)
.LBB0_119:
	s_or_b64 exec, exec, s[10:11]
	v_cvt_f32_u32_e32 v4, v1
	s_waitcnt vmcnt(0)
	v_readfirstlane_b32 s3, v3
	s_add_u32 s10, s56, 0x1ecb3500
	s_addc_u32 s11, s57, 0
	v_rcp_iflag_f32_e32 v4, v4
	v_add_u32_e32 v2, s3, v2
	v_add_u32_e32 v5, 1, v2
	s_mov_b64 s[12:13], -1
	v_mul_f32_e32 v3, 0x4f7ffffe, v4
	v_cvt_u32_f32_e32 v3, v3
	v_sub_u32_e32 v4, 0, v1
	v_mul_lo_u32 v4, v4, v3
	v_mul_hi_u32 v4, v3, v4
	v_add_u32_e32 v3, v3, v4
	v_mul_hi_u32 v3, v2, v3
	v_mul_lo_u32 v4, v3, v1
	v_sub_u32_e32 v2, v2, v4
	v_add_u32_e32 v6, 1, v3
	v_cmp_ge_u32_e32 vcc, v2, v1
	v_sub_u32_e32 v4, v2, v1
	s_nop 0
	v_cndmask_b32_e32 v3, v3, v6, vcc
	v_cndmask_b32_e32 v2, v2, v4, vcc
	v_add_u32_e32 v4, 1, v3
	v_cmp_ge_u32_e32 vcc, v2, v1
	s_nop 1
	v_cndmask_b32_e32 v4, v3, v4, vcc
	v_mul_lo_u32 v2, v1, v4
	v_add_u32_e32 v1, v2, v1
	v_cmp_ne_u32_e32 vcc, v5, v1
	s_mov_b64 s[100:101], vcc
	v_mov_b64_e32 v[2:3], s[10:11]
	s_and_saveexec_b64 s[8:9], vcc
	s_cbranch_execz .LBB0_131
	v_mov_b32_e32 v1, 0
	global_load_dword v2, v1, s[10:11] sc1
	s_mov_b64 s[16:17], 0
	s_waitcnt vmcnt(0)
	v_cmp_eq_u32_e32 vcc, v2, v4
	s_and_saveexec_b64 s[14:15], vcc
	s_cbranch_execz .LBB0_130
	s_add_u32 s12, s56, 0x1ecb0200
	s_addc_u32 s13, s57, 0
	s_mov_b32 s3, 1
	s_branch .LBB0_123

.LBB0_133:
	s_or_b64 exec, exec, s[8:9]
	v_mov_b32_e32 v1, 0x2000
	v_mov_b32_e32 v2, 1
	s_waitcnt vmcnt(0)
	s_and_b64 vcc, exec, s[100:101]
	s_cbranch_vccnz .Lmy_nl_1
	v_mov_b32_e32 v3, 0x2800
	global_atomic_add v1, v2, s[34:35] offset:1024
	global_atomic_add v1, v2, s[34:35] offset:1280
	global_atomic_add v1, v2, s[34:35] offset:1536
	global_atomic_add v1, v2, s[34:35] offset:1792
	global_atomic_add v1, v2, s[34:35] offset:2048
	global_atomic_add v1, v2, s[34:35] offset:2304
	global_atomic_add v1, v2, s[34:35] offset:2560
	global_atomic_add v1, v2, s[34:35] offset:2816
	global_atomic_add v3, v2, s[34:35] offset:1024
	global_atomic_add v3, v2, s[34:35] offset:1280
	global_atomic_add v3, v2, s[34:35] offset:1536
	global_atomic_add v3, v2, s[34:35] offset:1792
	global_atomic_add v3, v2, s[34:35] offset:2048
	global_atomic_add v3, v2, s[34:35] offset:2304
	global_atomic_add v3, v2, s[34:35] offset:2560
	global_atomic_add v3, v2, s[34:35] offset:2816

.LBB0_625:
	s_or_b64 exec, exec, s[8:9]
	v_cvt_f32_u32_e32 v5, v2
	s_waitcnt vmcnt(0)
	v_readfirstlane_b32 s3, v4
	s_add_u32 s8, s56, 0x1ecb3500
	s_addc_u32 s9, s57, 0
	v_rcp_iflag_f32_e32 v5, v5
	v_add_u32_e32 v3, s3, v3
	v_add_u32_e32 v6, 1, v3
	s_mov_b64 s[10:11], -1
	v_mul_f32_e32 v4, 0x4f7ffffe, v5
	v_cvt_u32_f32_e32 v4, v4
	v_sub_u32_e32 v5, 0, v2
	v_mul_lo_u32 v5, v5, v4
	v_mul_hi_u32 v5, v4, v5
	v_add_u32_e32 v4, v4, v5
	v_mul_hi_u32 v4, v3, v4
	v_mul_lo_u32 v5, v4, v2
	v_sub_u32_e32 v3, v3, v5
	v_add_u32_e32 v7, 1, v4
	v_cmp_ge_u32_e32 vcc, v3, v2
	v_sub_u32_e32 v5, v3, v2
	s_nop 0
	v_cndmask_b32_e32 v4, v4, v7, vcc
	v_cndmask_b32_e32 v3, v3, v5, vcc
	v_add_u32_e32 v5, 1, v4
	v_cmp_ge_u32_e32 vcc, v3, v2
	s_nop 1
	v_cndmask_b32_e32 v4, v4, v5, vcc
	v_mul_lo_u32 v3, v2, v4
	v_add_u32_e32 v2, v3, v2
	v_cmp_ne_u32_e32 vcc, v6, v2
	s_mov_b64 s[100:101], vcc
	v_mov_b64_e32 v[2:3], s[8:9]
	s_and_saveexec_b64 s[6:7], vcc
	s_cbranch_execz .LBB0_637
	v_mov_b32_e32 v2, 0
	global_load_dword v3, v2, s[8:9] sc1
	s_mov_b64 s[14:15], 0
	s_waitcnt vmcnt(0)
	v_cmp_eq_u32_e32 vcc, v3, v4
	s_and_saveexec_b64 s[12:13], vcc
	s_cbranch_execz .LBB0_636
	s_add_u32 s10, s56, 0x1ecb0200
	s_addc_u32 s11, s57, 0
	s_mov_b32 s3, 1
	s_branch .LBB0_629

.LBB0_639:
	s_or_b64 exec, exec, s[6:7]
	v_mov_b32_e32 v2, 0x2000
	v_mov_b32_e32 v3, 1
	s_waitcnt vmcnt(0)
	s_and_b64 vcc, exec, s[100:101]
	s_cbranch_vccnz .Lmy_nl_6
	v_mov_b32_e32 v4, 0x2800
	global_atomic_add v2, v3, s[34:35] offset:1024
	global_atomic_add v2, v3, s[34:35] offset:1280
	global_atomic_add v2, v3, s[34:35] offset:1536
	global_atomic_add v2, v3, s[34:35] offset:1792
	global_atomic_add v2, v3, s[34:35] offset:2048
	global_atomic_add v2, v3, s[34:35] offset:2304
	global_atomic_add v2, v3, s[34:35] offset:2560
	global_atomic_add v2, v3, s[34:35] offset:2816
	global_atomic_add v4, v3, s[34:35] offset:1024
	global_atomic_add v4, v3, s[34:35] offset:1280
	global_atomic_add v4, v3, s[34:35] offset:1536
	global_atomic_add v4, v3, s[34:35] offset:1792
	global_atomic_add v4, v3, s[34:35] offset:2048
	global_atomic_add v4, v3, s[34:35] offset:2304
	global_atomic_add v4, v3, s[34:35] offset:2560
	global_atomic_add v4, v3, s[34:35] offset:2816

.LBB0_802:
	s_or_b64 exec, exec, s[10:11]
	v_cvt_f32_u32_e32 v5, v2
	s_waitcnt vmcnt(0)
	v_readfirstlane_b32 s3, v4
	s_add_u32 s10, s56, 0x1ecb3500
	s_addc_u32 s11, s57, 0
	v_rcp_iflag_f32_e32 v5, v5
	v_add_u32_e32 v3, s3, v3
	v_add_u32_e32 v6, 1, v3
	s_mov_b64 s[12:13], -1
	v_mul_f32_e32 v4, 0x4f7ffffe, v5
	v_cvt_u32_f32_e32 v4, v4
	v_sub_u32_e32 v5, 0, v2
	v_mul_lo_u32 v5, v5, v4
	v_mul_hi_u32 v5, v4, v5
	v_add_u32_e32 v4, v4, v5
	v_mul_hi_u32 v4, v3, v4
	v_mul_lo_u32 v5, v4, v2
	v_sub_u32_e32 v3, v3, v5
	v_add_u32_e32 v7, 1, v4
	v_cmp_ge_u32_e32 vcc, v3, v2
	v_sub_u32_e32 v5, v3, v2
	s_nop 0
	v_cndmask_b32_e32 v4, v4, v7, vcc
	v_cndmask_b32_e32 v3, v3, v5, vcc
	v_add_u32_e32 v5, 1, v4
	v_cmp_ge_u32_e32 vcc, v3, v2
	s_nop 1
	v_cndmask_b32_e32 v4, v4, v5, vcc
	v_mul_lo_u32 v3, v2, v4
	v_add_u32_e32 v2, v3, v2
	v_cmp_ne_u32_e32 vcc, v6, v2
	s_mov_b64 s[100:101], vcc
	v_mov_b64_e32 v[2:3], s[10:11]
	s_and_saveexec_b64 s[8:9], vcc
	s_cbranch_execz .LBB0_814
	v_mov_b32_e32 v2, 0
	global_load_dword v3, v2, s[10:11] sc1
	s_mov_b64 s[16:17], 0
	s_waitcnt vmcnt(0)
	v_cmp_eq_u32_e32 vcc, v3, v4
	s_and_saveexec_b64 s[14:15], vcc
	s_cbranch_execz .LBB0_813
	s_add_u32 s12, s56, 0x1ecb0200
	s_addc_u32 s13, s57, 0
	s_mov_b32 s3, 1
	s_branch .LBB0_806

.LBB0_816:
	s_or_b64 exec, exec, s[8:9]
	v_mov_b32_e32 v2, 0x2000
	v_mov_b32_e32 v3, 1
	s_waitcnt vmcnt(0)
	s_and_b64 vcc, exec, s[100:101]
	s_cbranch_vccnz .Lmy_nl_8
	v_mov_b32_e32 v4, 0x2800
	global_atomic_add v2, v3, s[34:35] offset:1024
	global_atomic_add v2, v3, s[34:35] offset:1280
	global_atomic_add v2, v3, s[34:35] offset:1536
	global_atomic_add v2, v3, s[34:35] offset:1792
	global_atomic_add v2, v3, s[34:35] offset:2048
	global_atomic_add v2, v3, s[34:35] offset:2304
	global_atomic_add v2, v3, s[34:35] offset:2560
	global_atomic_add v2, v3, s[34:35] offset:2816
	global_atomic_add v4, v3, s[34:35] offset:1024
	global_atomic_add v4, v3, s[34:35] offset:1280
	global_atomic_add v4, v3, s[34:35] offset:1536
	global_atomic_add v4, v3, s[34:35] offset:1792
	global_atomic_add v4, v3, s[34:35] offset:2048
	global_atomic_add v4, v3, s[34:35] offset:2304
	global_atomic_add v4, v3, s[34:35] offset:2560
	global_atomic_add v4, v3, s[34:35] offset:2816

.LBB0_1128:
	s_or_b64 exec, exec, s[8:9]
	v_cvt_f32_u32_e32 v4, v1
	s_waitcnt vmcnt(0)
	v_readfirstlane_b32 s3, v3
	s_add_u32 s8, s56, 0x1ecb3500
	s_addc_u32 s9, s57, 0
	v_rcp_iflag_f32_e32 v4, v4
	v_add_u32_e32 v2, s3, v2
	v_add_u32_e32 v5, 1, v2
	s_mov_b64 s[10:11], -1
	v_mul_f32_e32 v3, 0x4f7ffffe, v4
	v_cvt_u32_f32_e32 v3, v3
	v_sub_u32_e32 v4, 0, v1
	v_mul_lo_u32 v4, v4, v3
	v_mul_hi_u32 v4, v3, v4
	v_add_u32_e32 v3, v3, v4
	v_mul_hi_u32 v3, v2, v3
	v_mul_lo_u32 v4, v3, v1
	v_sub_u32_e32 v2, v2, v4
	v_add_u32_e32 v6, 1, v3
	v_cmp_ge_u32_e32 vcc, v2, v1
	v_sub_u32_e32 v4, v2, v1
	s_nop 0
	v_cndmask_b32_e32 v3, v3, v6, vcc
	v_cndmask_b32_e32 v2, v2, v4, vcc
	v_add_u32_e32 v4, 1, v3
	v_cmp_ge_u32_e32 vcc, v2, v1
	s_nop 1
	v_cndmask_b32_e32 v4, v3, v4, vcc
	v_mul_lo_u32 v2, v1, v4
	v_add_u32_e32 v1, v2, v1
	v_cmp_ne_u32_e32 vcc, v5, v1
	s_mov_b64 s[100:101], vcc
	v_mov_b64_e32 v[2:3], s[8:9]
	s_and_saveexec_b64 s[6:7], vcc
	s_cbranch_execz .LBB0_1140
	v_mov_b32_e32 v1, 0
	global_load_dword v2, v1, s[8:9] sc1
	s_mov_b64 s[14:15], 0
	s_waitcnt vmcnt(0)
	v_cmp_eq_u32_e32 vcc, v2, v4
	s_and_saveexec_b64 s[12:13], vcc
	s_cbranch_execz .LBB0_1139
	s_add_u32 s10, s56, 0x1ecb0200
	s_addc_u32 s11, s57, 0
	s_mov_b32 s3, 1
	s_branch .LBB0_1132

.LBB0_1142:
	s_or_b64 exec, exec, s[6:7]
	v_mov_b32_e32 v1, 0x2000
	v_mov_b32_e32 v2, 1
	s_waitcnt vmcnt(0)
	s_and_b64 vcc, exec, s[100:101]
	s_cbranch_vccnz .Lmy_nl_12
	v_mov_b32_e32 v3, 0x2800
	global_atomic_add v1, v2, s[34:35] offset:1024
	global_atomic_add v1, v2, s[34:35] offset:1280
	global_atomic_add v1, v2, s[34:35] offset:1536
	global_atomic_add v1, v2, s[34:35] offset:1792
	global_atomic_add v1, v2, s[34:35] offset:2048
	global_atomic_add v1, v2, s[34:35] offset:2304
	global_atomic_add v1, v2, s[34:35] offset:2560
	global_atomic_add v1, v2, s[34:35] offset:2816
	global_atomic_add v3, v2, s[34:35] offset:1024
	global_atomic_add v3, v2, s[34:35] offset:1280
	global_atomic_add v3, v2, s[34:35] offset:1536
	global_atomic_add v3, v2, s[34:35] offset:1792
	global_atomic_add v3, v2, s[34:35] offset:2048
	global_atomic_add v3, v2, s[34:35] offset:2304
	global_atomic_add v3, v2, s[34:35] offset:2560
	global_atomic_add v3, v2, s[34:35] offset:2816
